# speedup vs baseline: 1.0137x; 1.0137x over previous
; __device__ __forceinline__ unsigned xb_ld(unsigned* p)              { return __hip_atomic_load(p, __ATOMIC_RELAXED, __HIP_MEMORY_SCOPE_AGENT); }
; __device__ __forceinline__ unsigned xb_add(unsigned* p, unsigned v) { return __hip_atomic_fetch_add(p, v, __ATOMIC_RELAXED, __HIP_MEMORY_SCOPE_AGENT); }
; #define XB_SPIN(cond, bar) do { unsigned _sp = 0; while (cond) { __builtin_amdgcn_s_sleep(1); \
;     if ((++_sp & 255u) == 0u) { if (xb_ld(&(bar)[XB_TMO])) break; if (_sp > XB_SPIN_CAP) { atomicAdd(&(bar)[XB_TMO], 1u); break; } } } } while (0)
; __device__ __forceinline__ void xcd_barrier() {
;     ...
;     const unsigned old = xb_add(&bar[XB_XSUB(bx)], 1u);
;     const unsigned gen = old / nloc;
;     if (old + 1u == (gen + 1u) * nloc) {
;       __builtin_amdgcn_fence(__ATOMIC_RELEASE, "agent");
;       asm volatile("s_waitcnt vmcnt(0)" ::: "memory");
;       const unsigned og = xb_add(&bar[XB_TOP], 1u);
;       const unsigned tg = og / nx;
;       if (og + 1u == (tg + 1u) * nx) xb_add(&bar[XB_TOPGEN], 1u);
;       else XB_SPIN(xb_ld(&bar[XB_TOPGEN]) == tg, bar);
;       __builtin_amdgcn_fence(__ATOMIC_ACQUIRE, "agent");
;       xb_add(&bar[XB_XGEN(bx)], 1u);
;     } else {
;       XB_SPIN(xb_ld(&bar[XB_XGEN(bx)]) == gen, bar);
;       __builtin_amdgcn_fence(__ATOMIC_ACQUIRE, "agent");
;     }
.LBB0_44:
	s_or_b64 exec, exec, s[10:11]
	v_cvt_f32_u32_e32 v6, v3
	s_waitcnt vmcnt(0)
	v_readfirstlane_b32 s8, v2
	v_sub_u32_e32 v2, 0, v3
	v_rcp_iflag_f32_e32 v6, v6
	v_add_u32_e32 v5, s8, v5
	v_mul_f32_e32 v6, 0x4f7ffffe, v6
	v_cvt_u32_f32_e32 v6, v6
	v_mul_lo_u32 v2, v2, v6
	v_mul_hi_u32 v2, v6, v2
	v_add_u32_e32 v2, v6, v2
	v_mul_hi_u32 v2, v5, v2
	v_mul_lo_u32 v6, v2, v3
	v_sub_u32_e32 v6, v5, v6
	v_add_u32_e32 v7, 1, v2
	v_cmp_ge_u32_e32 vcc, v6, v3
	v_add_u32_e32 v5, 1, v5
	s_nop 0
	v_cndmask_b32_e32 v2, v2, v7, vcc
	v_sub_u32_e32 v7, v6, v3
	v_cndmask_b32_e32 v6, v6, v7, vcc
	v_add_u32_e32 v7, 1, v2
	v_cmp_ge_u32_e32 vcc, v6, v3
	s_nop 1
	v_cndmask_b32_e32 v2, v2, v7, vcc
	v_mul_lo_u32 v6, v3, v2
	v_add_u32_e32 v3, v6, v3
	v_cmp_ne_u32_e32 vcc, v5, v3
	s_and_saveexec_b64 s[8:9], vcc
	s_xor_b64 s[8:9], exec, s[8:9]
	s_cbranch_execz .LBB0_58
	buffer_inv sc1
	s_add_i32 s10, s27, 0x900
	s_mov_b32 s11, 0
	s_lshl_b64 s[10:11], s[10:11], 2
	s_add_u32 s14, s3, s10
	s_addc_u32 s15, s26, s11
	v_mov_b32_e32 v3, 0
	global_load_dword v4, v3, s[14:15] sc1
	s_waitcnt vmcnt(0)
	v_cmp_eq_u32_e32 vcc, v4, v2
	s_and_saveexec_b64 s[10:11], vcc
	s_cbranch_execz .LBB0_57
	s_add_u32 s12, s6, 0xfc00200
	s_addc_u32 s13, s7, 0
	s_mov_b32 s28, 1
	s_mov_b64 s[16:17], 0
	s_branch .LBB0_48

; __device__ __forceinline__ unsigned xb_ld(unsigned* p)              { return __hip_atomic_load(p, __ATOMIC_RELAXED, __HIP_MEMORY_SCOPE_AGENT); }
; __device__ __forceinline__ unsigned xb_add(unsigned* p, unsigned v) { return __hip_atomic_fetch_add(p, v, __ATOMIC_RELAXED, __HIP_MEMORY_SCOPE_AGENT); }
; #define XB_SPIN(cond, bar) do { unsigned _sp = 0; while (cond) { __builtin_amdgcn_s_sleep(1); \
;     if ((++_sp & 255u) == 0u) { if (xb_ld(&(bar)[XB_TMO])) break; if (_sp > XB_SPIN_CAP) { atomicAdd(&(bar)[XB_TMO], 1u); break; } } } } while (0)
; __device__ __forceinline__ void xcd_barrier() {
;     ...
;     if (old + 1u == (gen + 1u) * nloc) {
;       __builtin_amdgcn_fence(__ATOMIC_RELEASE, "agent");
;       asm volatile("s_waitcnt vmcnt(0)" ::: "memory");
;       const unsigned og = xb_add(&bar[XB_TOP], 1u);
;       const unsigned tg = og / nx;
;       if (og + 1u == (tg + 1u) * nx) xb_add(&bar[XB_TOPGEN], 1u);
;       else XB_SPIN(xb_ld(&bar[XB_TOPGEN]) == tg, bar);
;       __builtin_amdgcn_fence(__ATOMIC_ACQUIRE, "agent");
;       xb_add(&bar[XB_XGEN(bx)], 1u);
;     } else {
;       XB_SPIN(xb_ld(&bar[XB_XGEN(bx)]) == gen, bar);
;       __builtin_amdgcn_fence(__ATOMIC_ACQUIRE, "agent");
.LBB0_57:
	s_or_b64 exec, exec, s[10:11]
	s_waitcnt vmcnt(0)
.LBB0_58:
	s_andn2_saveexec_b64 s[8:9], s[8:9]
	s_cbranch_execz .LBB0_78
	s_mov_b64 s[8:9], exec
	buffer_wbl2 sc1
	s_waitcnt vmcnt(0)
	v_mbcnt_lo_u32_b32 v2, s8, 0
	v_mbcnt_hi_u32_b32 v2, s9, v2
	v_cmp_eq_u32_e32 vcc, 0, v2
	s_and_saveexec_b64 s[10:11], vcc
	s_cbranch_execz .LBB0_61
	s_bcnt1_i32_b64 s8, s[8:9]
	v_mov_b32_e32 v3, 0xfc03000
	v_mov_b32_e32 v5, s8
	global_atomic_add v3, v3, v5, s[6:7] offset:1024 sc0

; __device__ __forceinline__ unsigned xb_ld(unsigned* p)              { return __hip_atomic_load(p, __ATOMIC_RELAXED, __HIP_MEMORY_SCOPE_AGENT); }
; __device__ __forceinline__ unsigned xb_add(unsigned* p, unsigned v) { return __hip_atomic_fetch_add(p, v, __ATOMIC_RELAXED, __HIP_MEMORY_SCOPE_AGENT); }
; #define XB_SPIN(cond, bar) do { unsigned _sp = 0; while (cond) { __builtin_amdgcn_s_sleep(1); \
;     if ((++_sp & 255u) == 0u) { if (xb_ld(&(bar)[XB_TMO])) break; if (_sp > XB_SPIN_CAP) { atomicAdd(&(bar)[XB_TMO], 1u); break; } } } } while (0)
; __device__ __forceinline__ void xcd_barrier() {
;     ...
;     if (old + 1u == (gen + 1u) * nloc) {
;       __builtin_amdgcn_fence(__ATOMIC_RELEASE, "agent");
;       asm volatile("s_waitcnt vmcnt(0)" ::: "memory");
;       const unsigned og = xb_add(&bar[XB_TOP], 1u);
;       const unsigned tg = og / nx;
;       if (og + 1u == (tg + 1u) * nx) xb_add(&bar[XB_TOPGEN], 1u);
;       else XB_SPIN(xb_ld(&bar[XB_TOPGEN]) == tg, bar);
;       __builtin_amdgcn_fence(__ATOMIC_ACQUIRE, "agent");
;       xb_add(&bar[XB_XGEN(bx)], 1u);
;     } else {
;       XB_SPIN(xb_ld(&bar[XB_XGEN(bx)]) == gen, bar);
;       __builtin_amdgcn_fence(__ATOMIC_ACQUIRE, "agent");
.LBB0_199:
	s_or_b64 exec, exec, s[10:11]
	s_waitcnt vmcnt(0)
.LBB0_200:
	s_andn2_saveexec_b64 s[8:9], s[8:9]
	s_cbranch_execz .LBB0_220
	s_mov_b64 s[8:9], exec
	buffer_wbl2 sc1
	s_waitcnt vmcnt(0)
	v_mbcnt_lo_u32_b32 v2, s8, 0
	v_mbcnt_hi_u32_b32 v2, s9, v2
	v_cmp_eq_u32_e32 vcc, 0, v2
	s_and_saveexec_b64 s[10:11], vcc
	s_cbranch_execz .LBB0_203
	s_bcnt1_i32_b64 s8, s[8:9]
	v_mov_b32_e32 v3, 0xfc03000
	v_mov_b32_e32 v5, s8
	global_atomic_add v3, v3, v5, s[6:7] offset:1024 sc0

; __device__ __forceinline__ unsigned xb_ld(unsigned* p)              { return __hip_atomic_load(p, __ATOMIC_RELAXED, __HIP_MEMORY_SCOPE_AGENT); }
; __device__ __forceinline__ unsigned xb_add(unsigned* p, unsigned v) { return __hip_atomic_fetch_add(p, v, __ATOMIC_RELAXED, __HIP_MEMORY_SCOPE_AGENT); }
; #define XB_SPIN(cond, bar) do { unsigned _sp = 0; while (cond) { __builtin_amdgcn_s_sleep(1); \
;     if ((++_sp & 255u) == 0u) { if (xb_ld(&(bar)[XB_TMO])) break; if (_sp > XB_SPIN_CAP) { atomicAdd(&(bar)[XB_TMO], 1u); break; } } } } while (0)
; __device__ __forceinline__ void xcd_barrier() {
;     ...
;     if (old + 1u == (gen + 1u) * nloc) {
;       __builtin_amdgcn_fence(__ATOMIC_RELEASE, "agent");
;       asm volatile("s_waitcnt vmcnt(0)" ::: "memory");
;       const unsigned og = xb_add(&bar[XB_TOP], 1u);
;       const unsigned tg = og / nx;
;       if (og + 1u == (tg + 1u) * nx) xb_add(&bar[XB_TOPGEN], 1u);
;       else XB_SPIN(xb_ld(&bar[XB_TOPGEN]) == tg, bar);
;       __builtin_amdgcn_fence(__ATOMIC_ACQUIRE, "agent");
;       xb_add(&bar[XB_XGEN(bx)], 1u);
;     } else {
;       XB_SPIN(xb_ld(&bar[XB_XGEN(bx)]) == gen, bar);
;       __builtin_amdgcn_fence(__ATOMIC_ACQUIRE, "agent");
.LBB0_315:
	s_or_b64 exec, exec, s[10:11]
	s_waitcnt vmcnt(0)
.LBB0_316:
	s_andn2_saveexec_b64 s[8:9], s[8:9]
	s_cbranch_execz .LBB0_336
	s_mov_b64 s[8:9], exec
	buffer_wbl2 sc1
	s_waitcnt vmcnt(0)
	v_mbcnt_lo_u32_b32 v2, s8, 0
	v_mbcnt_hi_u32_b32 v2, s9, v2
	v_cmp_eq_u32_e32 vcc, 0, v2
	s_and_saveexec_b64 s[10:11], vcc
	s_cbranch_execz .LBB0_319
	s_bcnt1_i32_b64 s8, s[8:9]
	v_mov_b32_e32 v3, 0xfc03000
	v_mov_b32_e32 v5, s8
	global_atomic_add v3, v3, v5, s[6:7] offset:1024 sc0

; __device__ __forceinline__ unsigned xb_ld(unsigned* p)              { return __hip_atomic_load(p, __ATOMIC_RELAXED, __HIP_MEMORY_SCOPE_AGENT); }
; __device__ __forceinline__ unsigned xb_add(unsigned* p, unsigned v) { return __hip_atomic_fetch_add(p, v, __ATOMIC_RELAXED, __HIP_MEMORY_SCOPE_AGENT); }
; #define XB_SPIN(cond, bar) do { unsigned _sp = 0; while (cond) { __builtin_amdgcn_s_sleep(1); \
;     if ((++_sp & 255u) == 0u) { if (xb_ld(&(bar)[XB_TMO])) break; if (_sp > XB_SPIN_CAP) { atomicAdd(&(bar)[XB_TMO], 1u); break; } } } } while (0)
; __device__ __forceinline__ void xcd_barrier() {
;     ...
;     if (old + 1u == (gen + 1u) * nloc) {
;       __builtin_amdgcn_fence(__ATOMIC_RELEASE, "agent");
;       asm volatile("s_waitcnt vmcnt(0)" ::: "memory");
;       const unsigned og = xb_add(&bar[XB_TOP], 1u);
;       const unsigned tg = og / nx;
;       if (og + 1u == (tg + 1u) * nx) xb_add(&bar[XB_TOPGEN], 1u);
;       else XB_SPIN(xb_ld(&bar[XB_TOPGEN]) == tg, bar);
;       __builtin_amdgcn_fence(__ATOMIC_ACQUIRE, "agent");
;       xb_add(&bar[XB_XGEN(bx)], 1u);
;     } else {
;       XB_SPIN(xb_ld(&bar[XB_XGEN(bx)]) == gen, bar);
;       __builtin_amdgcn_fence(__ATOMIC_ACQUIRE, "agent");
.LBB0_396:
	s_or_b64 exec, exec, s[10:11]
	s_waitcnt vmcnt(0)
.LBB0_397:
	s_andn2_saveexec_b64 s[8:9], s[8:9]
	s_cbranch_execz .LBB0_417
	s_mov_b64 s[8:9], exec
	buffer_wbl2 sc1
	s_waitcnt vmcnt(0)
	v_mbcnt_lo_u32_b32 v2, s8, 0
	v_mbcnt_hi_u32_b32 v2, s9, v2
	v_cmp_eq_u32_e32 vcc, 0, v2
	s_and_saveexec_b64 s[10:11], vcc
	s_cbranch_execz .LBB0_400
	s_bcnt1_i32_b64 s8, s[8:9]
	v_mov_b32_e32 v3, 0xfc03000
	v_mov_b32_e32 v5, s8
	global_atomic_add v3, v3, v5, s[6:7] offset:1024 sc0

; __device__ __forceinline__ unsigned xb_ld(unsigned* p)              { return __hip_atomic_load(p, __ATOMIC_RELAXED, __HIP_MEMORY_SCOPE_AGENT); }
; __device__ __forceinline__ unsigned xb_add(unsigned* p, unsigned v) { return __hip_atomic_fetch_add(p, v, __ATOMIC_RELAXED, __HIP_MEMORY_SCOPE_AGENT); }
; #define XB_SPIN(cond, bar) do { unsigned _sp = 0; while (cond) { __builtin_amdgcn_s_sleep(1); \
;     if ((++_sp & 255u) == 0u) { if (xb_ld(&(bar)[XB_TMO])) break; if (_sp > XB_SPIN_CAP) { atomicAdd(&(bar)[XB_TMO], 1u); break; } } } } while (0)
; __device__ __forceinline__ void xcd_barrier() {
;     ...
;     const unsigned old = xb_add(&bar[XB_XSUB(bx)], 1u);
;     const unsigned gen = old / nloc;
;     if (old + 1u == (gen + 1u) * nloc) {
;       __builtin_amdgcn_fence(__ATOMIC_RELEASE, "agent");
;       asm volatile("s_waitcnt vmcnt(0)" ::: "memory");
;       const unsigned og = xb_add(&bar[XB_TOP], 1u);
;       const unsigned tg = og / nx;
;       if (og + 1u == (tg + 1u) * nx) xb_add(&bar[XB_TOPGEN], 1u);
;       else XB_SPIN(xb_ld(&bar[XB_TOPGEN]) == tg, bar);
;       __builtin_amdgcn_fence(__ATOMIC_ACQUIRE, "agent");
;       xb_add(&bar[XB_XGEN(bx)], 1u);
;     } else {
;       XB_SPIN(xb_ld(&bar[XB_XGEN(bx)]) == gen, bar);
;       __builtin_amdgcn_fence(__ATOMIC_ACQUIRE, "agent");
;     }
.LBB0_667:
	s_or_b64 exec, exec, s[10:11]
	v_cvt_f32_u32_e32 v5, v3
	s_waitcnt vmcnt(0)
	v_readfirstlane_b32 s8, v2
	v_sub_u32_e32 v2, 0, v3
	v_rcp_iflag_f32_e32 v5, v5
	v_add_u32_e32 v6, s8, v1
	v_mul_f32_e32 v5, 0x4f7ffffe, v5
	v_cvt_u32_f32_e32 v5, v5
	v_mul_lo_u32 v1, v2, v5
	v_mul_hi_u32 v1, v5, v1
	v_add_u32_e32 v1, v5, v1
	v_mul_hi_u32 v1, v6, v1
	v_mul_lo_u32 v2, v1, v3
	v_sub_u32_e32 v2, v6, v2
	v_add_u32_e32 v5, 1, v1
	v_cmp_ge_u32_e32 vcc, v2, v3
	s_nop 1
	v_cndmask_b32_e32 v1, v1, v5, vcc
	v_sub_u32_e32 v5, v2, v3
	v_cndmask_b32_e32 v2, v2, v5, vcc
	v_add_u32_e32 v5, 1, v1
	v_cmp_ge_u32_e32 vcc, v2, v3
	v_add_u32_e32 v2, 1, v6
	s_nop 0
	v_cndmask_b32_e32 v1, v1, v5, vcc
	v_mul_lo_u32 v5, v3, v1
	v_add_u32_e32 v3, v5, v3
	v_cmp_ne_u32_e32 vcc, v2, v3
	s_and_saveexec_b64 s[8:9], vcc
	s_xor_b64 s[8:9], exec, s[8:9]
	s_cbranch_execz .LBB0_681
	buffer_inv sc1
	s_add_i32 s10, s27, 0x900
	s_mov_b32 s11, 0
	s_lshl_b64 s[10:11], s[10:11], 2
	s_add_u32 s14, s3, s10
	s_addc_u32 s15, s26, s11
	v_mov_b32_e32 v2, 0
	global_load_dword v3, v2, s[14:15] sc1
	s_waitcnt vmcnt(0)
	v_cmp_eq_u32_e32 vcc, v3, v1
	s_and_saveexec_b64 s[10:11], vcc
	s_cbranch_execz .LBB0_680
	s_add_u32 s12, s6, 0xfc00200
	s_addc_u32 s13, s7, 0
	s_mov_b32 s28, 1
	s_mov_b64 s[16:17], 0
	s_branch .LBB0_671

; __device__ __forceinline__ unsigned xb_ld(unsigned* p)              { return __hip_atomic_load(p, __ATOMIC_RELAXED, __HIP_MEMORY_SCOPE_AGENT); }
; __device__ __forceinline__ unsigned xb_add(unsigned* p, unsigned v) { return __hip_atomic_fetch_add(p, v, __ATOMIC_RELAXED, __HIP_MEMORY_SCOPE_AGENT); }
; #define XB_SPIN(cond, bar) do { unsigned _sp = 0; while (cond) { __builtin_amdgcn_s_sleep(1); \
;     if ((++_sp & 255u) == 0u) { if (xb_ld(&(bar)[XB_TMO])) break; if (_sp > XB_SPIN_CAP) { atomicAdd(&(bar)[XB_TMO], 1u); break; } } } } while (0)
; __device__ __forceinline__ void xcd_barrier() {
;     ...
;     if (old + 1u == (gen + 1u) * nloc) {
;       __builtin_amdgcn_fence(__ATOMIC_RELEASE, "agent");
;       asm volatile("s_waitcnt vmcnt(0)" ::: "memory");
;       const unsigned og = xb_add(&bar[XB_TOP], 1u);
;       const unsigned tg = og / nx;
;       if (og + 1u == (tg + 1u) * nx) xb_add(&bar[XB_TOPGEN], 1u);
;       else XB_SPIN(xb_ld(&bar[XB_TOPGEN]) == tg, bar);
;       __builtin_amdgcn_fence(__ATOMIC_ACQUIRE, "agent");
;       xb_add(&bar[XB_XGEN(bx)], 1u);
;     } else {
;       XB_SPIN(xb_ld(&bar[XB_XGEN(bx)]) == gen, bar);
;       __builtin_amdgcn_fence(__ATOMIC_ACQUIRE, "agent");
.LBB0_680:
	s_or_b64 exec, exec, s[10:11]
	s_waitcnt vmcnt(0)
.LBB0_681:
	s_andn2_saveexec_b64 s[8:9], s[8:9]
	s_cbranch_execz .LBB0_701
	s_mov_b64 s[8:9], exec
	buffer_wbl2 sc1
	s_waitcnt vmcnt(0)
	v_mbcnt_lo_u32_b32 v1, s8, 0
	v_mbcnt_hi_u32_b32 v1, s9, v1
	v_cmp_eq_u32_e32 vcc, 0, v1
	s_and_saveexec_b64 s[10:11], vcc
	s_cbranch_execz .LBB0_684
	s_bcnt1_i32_b64 s8, s[8:9]
	v_mov_b32_e32 v2, 0xfc03000
	v_mov_b32_e32 v3, s8
	global_atomic_add v2, v2, v3, s[6:7] offset:1024 sc0

; __device__ __forceinline__ unsigned xb_ld(unsigned* p)              { return __hip_atomic_load(p, __ATOMIC_RELAXED, __HIP_MEMORY_SCOPE_AGENT); }
; __device__ __forceinline__ unsigned xb_add(unsigned* p, unsigned v) { return __hip_atomic_fetch_add(p, v, __ATOMIC_RELAXED, __HIP_MEMORY_SCOPE_AGENT); }
; #define XB_SPIN(cond, bar) do { unsigned _sp = 0; while (cond) { __builtin_amdgcn_s_sleep(1); \
;     if ((++_sp & 255u) == 0u) { if (xb_ld(&(bar)[XB_TMO])) break; if (_sp > XB_SPIN_CAP) { atomicAdd(&(bar)[XB_TMO], 1u); break; } } } } while (0)
; __device__ __forceinline__ void xcd_barrier() {
;     ...
;     if (old + 1u == (gen + 1u) * nloc) {
;       __builtin_amdgcn_fence(__ATOMIC_RELEASE, "agent");
;       asm volatile("s_waitcnt vmcnt(0)" ::: "memory");
;       const unsigned og = xb_add(&bar[XB_TOP], 1u);
;       const unsigned tg = og / nx;
;       if (og + 1u == (tg + 1u) * nx) xb_add(&bar[XB_TOPGEN], 1u);
;       else XB_SPIN(xb_ld(&bar[XB_TOPGEN]) == tg, bar);
;       __builtin_amdgcn_fence(__ATOMIC_ACQUIRE, "agent");
;       xb_add(&bar[XB_XGEN(bx)], 1u);
;     } else {
;       XB_SPIN(xb_ld(&bar[XB_XGEN(bx)]) == gen, bar);
;       __builtin_amdgcn_fence(__ATOMIC_ACQUIRE, "agent");
.LBB0_736:
	s_or_b64 exec, exec, s[10:11]
	s_waitcnt vmcnt(0)
.LBB0_737:
	s_andn2_saveexec_b64 s[8:9], s[8:9]
	s_cbranch_execz .LBB0_757
	s_mov_b64 s[8:9], exec
	buffer_wbl2 sc1
	s_waitcnt vmcnt(0)
	v_mbcnt_lo_u32_b32 v1, s8, 0
	v_mbcnt_hi_u32_b32 v1, s9, v1
	v_cmp_eq_u32_e32 vcc, 0, v1
	s_and_saveexec_b64 s[10:11], vcc
	s_cbranch_execz .LBB0_740
	s_bcnt1_i32_b64 s8, s[8:9]
	v_mov_b32_e32 v2, 0xfc03000
	v_mov_b32_e32 v3, s8
	global_atomic_add v2, v2, v3, s[6:7] offset:1024 sc0

; __device__ __forceinline__ unsigned xb_ld(unsigned* p)              { return __hip_atomic_load(p, __ATOMIC_RELAXED, __HIP_MEMORY_SCOPE_AGENT); }
; __device__ __forceinline__ unsigned xb_add(unsigned* p, unsigned v) { return __hip_atomic_fetch_add(p, v, __ATOMIC_RELAXED, __HIP_MEMORY_SCOPE_AGENT); }
; #define XB_SPIN(cond, bar) do { unsigned _sp = 0; while (cond) { __builtin_amdgcn_s_sleep(1); \
;     if ((++_sp & 255u) == 0u) { if (xb_ld(&(bar)[XB_TMO])) break; if (_sp > XB_SPIN_CAP) { atomicAdd(&(bar)[XB_TMO], 1u); break; } } } } while (0)
; __device__ __forceinline__ void xcd_barrier() {
;     ...
;     if (old + 1u == (gen + 1u) * nloc) {
;       __builtin_amdgcn_fence(__ATOMIC_RELEASE, "agent");
;       asm volatile("s_waitcnt vmcnt(0)" ::: "memory");
;       const unsigned og = xb_add(&bar[XB_TOP], 1u);
;       const unsigned tg = og / nx;
;       if (og + 1u == (tg + 1u) * nx) xb_add(&bar[XB_TOPGEN], 1u);
;       else XB_SPIN(xb_ld(&bar[XB_TOPGEN]) == tg, bar);
;       __builtin_amdgcn_fence(__ATOMIC_ACQUIRE, "agent");
;       xb_add(&bar[XB_XGEN(bx)], 1u);
;     } else {
;       XB_SPIN(xb_ld(&bar[XB_XGEN(bx)]) == gen, bar);
;       __builtin_amdgcn_fence(__ATOMIC_ACQUIRE, "agent");
.LBB0_852:
	s_or_b64 exec, exec, s[10:11]
	s_waitcnt vmcnt(0)
.LBB0_853:
	s_andn2_saveexec_b64 s[8:9], s[8:9]
	s_cbranch_execz .LBB0_873
	s_mov_b64 s[8:9], exec
	buffer_wbl2 sc1
	s_waitcnt vmcnt(0)
	v_mbcnt_lo_u32_b32 v1, s8, 0
	v_mbcnt_hi_u32_b32 v1, s9, v1
	v_cmp_eq_u32_e32 vcc, 0, v1
	s_and_saveexec_b64 s[10:11], vcc
	s_cbranch_execz .LBB0_856
	s_bcnt1_i32_b64 s8, s[8:9]
	v_mov_b32_e32 v2, 0xfc03000
	v_mov_b32_e32 v3, s8
	global_atomic_add v2, v2, v3, s[6:7] offset:1024 sc0

; __device__ __forceinline__ unsigned xb_ld(unsigned* p)              { return __hip_atomic_load(p, __ATOMIC_RELAXED, __HIP_MEMORY_SCOPE_AGENT); }
; __device__ __forceinline__ unsigned xb_add(unsigned* p, unsigned v) { return __hip_atomic_fetch_add(p, v, __ATOMIC_RELAXED, __HIP_MEMORY_SCOPE_AGENT); }
; #define XB_SPIN(cond, bar) do { unsigned _sp = 0; while (cond) { __builtin_amdgcn_s_sleep(1); \
;     if ((++_sp & 255u) == 0u) { if (xb_ld(&(bar)[XB_TMO])) break; if (_sp > XB_SPIN_CAP) { atomicAdd(&(bar)[XB_TMO], 1u); break; } } } } while (0)
; __device__ __forceinline__ void xcd_barrier() {
;     ...
;     if (old + 1u == (gen + 1u) * nloc) {
;       __builtin_amdgcn_fence(__ATOMIC_RELEASE, "agent");
;       asm volatile("s_waitcnt vmcnt(0)" ::: "memory");
;       const unsigned og = xb_add(&bar[XB_TOP], 1u);
;       const unsigned tg = og / nx;
;       if (og + 1u == (tg + 1u) * nx) xb_add(&bar[XB_TOPGEN], 1u);
;       else XB_SPIN(xb_ld(&bar[XB_TOPGEN]) == tg, bar);
;       __builtin_amdgcn_fence(__ATOMIC_ACQUIRE, "agent");
;       xb_add(&bar[XB_XGEN(bx)], 1u);
;     } else {
;       XB_SPIN(xb_ld(&bar[XB_XGEN(bx)]) == gen, bar);
;       __builtin_amdgcn_fence(__ATOMIC_ACQUIRE, "agent");
.LBB0_1074:
	s_or_b64 exec, exec, s[10:11]
	s_waitcnt vmcnt(0)
.LBB0_1075:
	s_andn2_saveexec_b64 s[8:9], s[8:9]
	s_cbranch_execz .LBB0_1095
	s_mov_b64 s[8:9], exec
	buffer_wbl2 sc1
	s_waitcnt vmcnt(0)
	v_mbcnt_lo_u32_b32 v1, s8, 0
	v_mbcnt_hi_u32_b32 v1, s9, v1
	v_cmp_eq_u32_e32 vcc, 0, v1
	s_and_saveexec_b64 s[10:11], vcc
	s_cbranch_execz .LBB0_1078
	s_bcnt1_i32_b64 s8, s[8:9]
	v_mov_b32_e32 v2, 0xfc03000
	v_mov_b32_e32 v3, s8
	global_atomic_add v2, v2, v3, s[6:7] offset:1024 sc0

; __device__ __forceinline__ unsigned xb_ld(unsigned* p)              { return __hip_atomic_load(p, __ATOMIC_RELAXED, __HIP_MEMORY_SCOPE_AGENT); }
; __device__ __forceinline__ unsigned xb_add(unsigned* p, unsigned v) { return __hip_atomic_fetch_add(p, v, __ATOMIC_RELAXED, __HIP_MEMORY_SCOPE_AGENT); }
; #define XB_SPIN(cond, bar) do { unsigned _sp = 0; while (cond) { __builtin_amdgcn_s_sleep(1); \
;     if ((++_sp & 255u) == 0u) { if (xb_ld(&(bar)[XB_TMO])) break; if (_sp > XB_SPIN_CAP) { atomicAdd(&(bar)[XB_TMO], 1u); break; } } } } while (0)
; __device__ __forceinline__ void xcd_barrier() {
;     ...
;     if (old + 1u == (gen + 1u) * nloc) {
;       __builtin_amdgcn_fence(__ATOMIC_RELEASE, "agent");
;       asm volatile("s_waitcnt vmcnt(0)" ::: "memory");
;       const unsigned og = xb_add(&bar[XB_TOP], 1u);
;       const unsigned tg = og / nx;
;       if (og + 1u == (tg + 1u) * nx) xb_add(&bar[XB_TOPGEN], 1u);
;       else XB_SPIN(xb_ld(&bar[XB_TOPGEN]) == tg, bar);
;       __builtin_amdgcn_fence(__ATOMIC_ACQUIRE, "agent");
;       xb_add(&bar[XB_XGEN(bx)], 1u);
;     } else {
;       XB_SPIN(xb_ld(&bar[XB_XGEN(bx)]) == gen, bar);
;       __builtin_amdgcn_fence(__ATOMIC_ACQUIRE, "agent");
.LBB0_1190:
	s_or_b64 exec, exec, s[10:11]
	s_waitcnt vmcnt(0)
.LBB0_1191:
	s_andn2_saveexec_b64 s[8:9], s[8:9]
	s_cbranch_execz .LBB0_1211
	s_mov_b64 s[8:9], exec
	buffer_wbl2 sc1
	s_waitcnt vmcnt(0)
	v_mbcnt_lo_u32_b32 v1, s8, 0
	v_mbcnt_hi_u32_b32 v1, s9, v1
	v_cmp_eq_u32_e32 vcc, 0, v1
	s_and_saveexec_b64 s[10:11], vcc
	s_cbranch_execz .LBB0_1194
	s_bcnt1_i32_b64 s8, s[8:9]
	v_mov_b32_e32 v2, 0xfc03000
	v_mov_b32_e32 v3, s8
	global_atomic_add v2, v2, v3, s[6:7] offset:1024 sc0
